# row-scale loads of the P4/P9 sample-row GEMM issued with the operand loads instead of two serial round trips
# speedup vs baseline: 1.0066x; 1.0004x over previous
.LBB0_892:
	s_ashr_i32 s19, s21, 31
	s_lshr_b32 s19, s19, 30
	s_add_i32 s19, s21, s19
	s_ashr_i32 s19, s19, 2
	s_lshl_b32 s22, s19, 8
	s_sub_i32 s22, 0, s22
	v_add3_u32 v14, v49, v50, s22
	v_mov_b32_e32 v0, 1.0
	v_ashrrev_i32_e32 v15, 31, v14
	v_mov_b32_e32 v16, 1.0
	s_and_saveexec_b64 s[38:39], s[0:1]
	s_cbranch_execz .LBB0_894
	v_lshl_add_u64 v[136:137], v[14:15], 3, s[36:37]
	global_load_dwordx2 v[136:137], v[136:137], off
.LBB0_894:
	s_or_b64 exec, exec, s[38:39]
	s_and_saveexec_b64 s[38:39], s[42:43]
	s_cbranch_execz .LBB0_896
	v_add3_u32 v138, v51, v50, s22
	v_ashrrev_i32_e32 v139, 31, v138
	v_lshl_add_u64 v[138:139], v[138:139], 3, s[36:37]
	global_load_dwordx2 v[138:139], v[138:139], off
.LBB0_896:
	s_or_b64 exec, exec, s[38:39]
	s_lshl_b32 s19, s19, 6
	v_or_b32_e32 v4, s19, v17
	v_ashrrev_i32_e32 v5, 31, v4
	v_add_u32_e32 v2, s22, v50
	v_lshlrev_b64 v[4:5], 11, v[4:5]
	v_lshl_add_u64 v[24:25], v[12:13], 0, v[4:5]
	v_ashrrev_i32_e32 v3, 31, v2
	global_load_dwordx4 v[6:9], v[24:25], off
	v_lshlrev_b64 v[2:3], 11, v[2:3]
	v_lshl_add_u64 v[26:27], v[10:11], 0, v[2:3]
	v_add_co_u32_e32 v18, vcc, 0x8000, v26
	global_load_dwordx4 v[52:55], v[26:27], off
	s_nop 0
	v_addc_co_u32_e32 v19, vcc, 0, v27, vcc
	v_add_co_u32_e32 v20, vcc, 0x10000, v26
	global_load_dwordx4 v[56:59], v[18:19], off
	s_nop 0
	v_addc_co_u32_e32 v21, vcc, 0, v27, vcc
	v_add_co_u32_e32 v22, vcc, 0x18000, v26
	global_load_dwordx4 v[60:63], v[20:21], off
	global_load_dwordx4 v[2:5], v[24:25], off offset:64
	v_addc_co_u32_e32 v23, vcc, 0, v27, vcc
	global_load_dwordx4 v[68:71], v[22:23], off
	global_load_dwordx4 v[76:79], v[26:27], off offset:64
	global_load_dwordx4 v[80:83], v[18:19], off offset:64
	global_load_dwordx4 v[88:91], v[20:21], off offset:64
	s_waitcnt vmcnt(0)
	s_and_saveexec_b64 s[38:39], s[0:1]
	v_ffbh_u32_e32 v140, v137
	v_min_u32_e32 v140, 32, v140
	v_lshlrev_b64 v[136:137], v140, v[136:137]
	v_min_u32_e32 v136, 1, v136
	v_or_b32_e32 v136, v137, v136
	v_cvt_f32_u32_e32 v136, v136
	v_sub_u32_e32 v137, 32, v140
	v_ldexp_f32 v136, v136, v137
	v_fmamk_f32 v136, v136, 0x30800000, v207
	v_mul_f32_e32 v137, 0x4b800000, v136
	v_cmp_gt_f32_e32 vcc, s16, v136
	s_nop 1
	v_cndmask_b32_e32 v136, v136, v137, vcc
	v_rsq_f32_e32 v136, v136
	s_nop 0
	v_mul_f32_e32 v137, 0x45800000, v136
	v_cndmask_b32_e32 v16, v136, v137, vcc
	s_or_b64 exec, exec, s[38:39]
	s_and_saveexec_b64 s[38:39], s[42:43]
	v_ffbh_u32_e32 v140, v139
	v_min_u32_e32 v140, 32, v140
	v_lshlrev_b64 v[138:139], v140, v[138:139]
	v_min_u32_e32 v138, 1, v138
	v_or_b32_e32 v138, v139, v138
	v_cvt_f32_u32_e32 v138, v138
	v_sub_u32_e32 v139, 32, v140
	v_ldexp_f32 v138, v138, v139
	v_fmamk_f32 v138, v138, 0x30800000, v207
	v_mul_f32_e32 v139, 0x4b800000, v138
	v_cmp_gt_f32_e32 vcc, s16, v138
	s_nop 1
	v_cndmask_b32_e32 v138, v138, v139, vcc
	v_rsq_f32_e32 v138, v138
	s_nop 0
	v_mul_f32_e32 v139, 0x45800000, v138
	v_cndmask_b32_e32 v0, v138, v139, vcc
	s_or_b64 exec, exec, s[38:39]
	v_mfma_f32_16x16x32_bf16 v[28:31], v[6:9], v[52:55], 0
	v_mfma_f32_16x16x32_bf16 v[84:87], v[2:5], v[76:79], v[28:31]
	s_nop 6
	v_add_co_u32_e32 v28, vcc, s50, v24
	s_nop 1
	v_addc_co_u32_e32 v29, vcc, 0, v25, vcc
	v_add_co_u32_e32 v30, vcc, 0x10000, v24
	global_load_dwordx4 v[92:95], v[28:29], off
	s_nop 0
	v_addc_co_u32_e32 v31, vcc, 0, v25, vcc
	v_add_co_u32_e32 v32, vcc, 0x18000, v24
	global_load_dwordx4 v[108:111], v[30:31], off
	s_nop 0
	v_addc_co_u32_e32 v33, vcc, 0, v25, vcc
	global_load_dwordx4 v[124:127], v[32:33], off
	global_load_dwordx4 v[132:135], v[32:33], off offset:64
	v_mfma_f32_16x16x32_bf16 v[64:67], v[6:9], v[56:59], 0
	global_load_dwordx4 v[128:131], v[30:31], off offset:64
	v_mfma_f32_16x16x32_bf16 v[72:75], v[6:9], v[60:63], 0
	v_mfma_f32_16x16x32_bf16 v[6:9], v[6:9], v[68:71], 0
	s_waitcnt vmcnt(4)
	v_mfma_f32_16x16x32_bf16 v[96:99], v[92:95], v[52:55], 0
	v_mfma_f32_16x16x32_bf16 v[100:103], v[92:95], v[56:59], 0
	v_mfma_f32_16x16x32_bf16 v[104:107], v[92:95], v[60:63], 0
	v_mfma_f32_16x16x32_bf16 v[92:95], v[92:95], v[68:71], 0
	s_waitcnt vmcnt(3)
	v_mfma_f32_16x16x32_bf16 v[112:115], v[108:111], v[52:55], 0
	v_mfma_f32_16x16x32_bf16 v[116:119], v[108:111], v[56:59], 0
	v_mfma_f32_16x16x32_bf16 v[120:123], v[108:111], v[60:63], 0
	v_mfma_f32_16x16x32_bf16 v[108:111], v[108:111], v[68:71], 0
	s_waitcnt vmcnt(2)
	v_mfma_f32_16x16x32_bf16 v[52:55], v[124:127], v[52:55], 0
	v_mfma_f32_16x16x32_bf16 v[56:59], v[124:127], v[56:59], 0
	v_mfma_f32_16x16x32_bf16 v[60:63], v[124:127], v[60:63], 0
	v_mfma_f32_16x16x32_bf16 v[68:71], v[124:127], v[68:71], 0
	global_load_dwordx4 v[124:127], v[28:29], off offset:64
	v_mfma_f32_16x16x32_bf16 v[64:67], v[2:5], v[80:83], v[64:67]
	v_mfma_f32_16x16x32_bf16 v[72:75], v[2:5], v[88:91], v[72:75]
	s_waitcnt vmcnt(2)
	v_mfma_f32_16x16x32_bf16 v[52:55], v[132:135], v[76:79], v[52:55]
	v_mfma_f32_16x16x32_bf16 v[56:59], v[132:135], v[80:83], v[56:59]
	v_mfma_f32_16x16x32_bf16 v[60:63], v[132:135], v[88:91], v[60:63]
	s_waitcnt vmcnt(0)
	v_mfma_f32_16x16x32_bf16 v[96:99], v[124:127], v[76:79], v[96:99]
	v_mfma_f32_16x16x32_bf16 v[100:103], v[124:127], v[80:83], v[100:103]
	v_mfma_f32_16x16x32_bf16 v[112:115], v[128:131], v[76:79], v[112:115]
	v_mfma_f32_16x16x32_bf16 v[116:119], v[128:131], v[80:83], v[116:119]
	v_mfma_f32_16x16x32_bf16 v[76:79], v[124:127], v[88:91], v[104:107]
	v_mfma_f32_16x16x32_bf16 v[80:83], v[128:131], v[88:91], v[120:123]
	global_load_dwordx4 v[88:91], v[22:23], off offset:64
	s_nop 0
	global_load_dwordx4 v[104:107], v[24:25], off offset:128
	s_waitcnt vmcnt(1)
	v_mfma_f32_16x16x32_bf16 v[2:5], v[2:5], v[88:91], v[6:9]
	global_load_dwordx4 v[120:123], v[30:31], off offset:128
	v_mfma_f32_16x16x32_bf16 v[6:9], v[124:127], v[88:91], v[92:95]
	global_load_dwordx4 v[124:127], v[32:33], off offset:128
	v_mfma_f32_16x16x32_bf16 v[92:95], v[128:131], v[88:91], v[108:111]
	v_mfma_f32_16x16x32_bf16 v[68:71], v[132:135], v[88:91], v[68:71]
	global_load_dwordx4 v[88:91], v[26:27], off offset:128
	s_nop 0
	global_load_dwordx4 v[108:111], v[28:29], off offset:128
	s_waitcnt vmcnt(1)
	v_mfma_f32_16x16x32_bf16 v[84:87], v[104:107], v[88:91], v[84:87]
	s_waitcnt vmcnt(0)
	v_mfma_f32_16x16x32_bf16 v[96:99], v[108:111], v[88:91], v[96:99]
	v_mfma_f32_16x16x32_bf16 v[112:115], v[120:123], v[88:91], v[112:115]
	v_mfma_f32_16x16x32_bf16 v[52:55], v[124:127], v[88:91], v[52:55]
	global_load_dwordx4 v[88:91], v[18:19], off offset:128
	s_waitcnt vmcnt(0)
	v_mfma_f32_16x16x32_bf16 v[64:67], v[104:107], v[88:91], v[64:67]
	v_mfma_f32_16x16x32_bf16 v[100:103], v[108:111], v[88:91], v[100:103]
	v_mfma_f32_16x16x32_bf16 v[116:119], v[120:123], v[88:91], v[116:119]
	v_mfma_f32_16x16x32_bf16 v[56:59], v[124:127], v[88:91], v[56:59]
	global_load_dwordx4 v[88:91], v[20:21], off offset:128
	s_waitcnt vmcnt(0)
	v_mfma_f32_16x16x32_bf16 v[72:75], v[104:107], v[88:91], v[72:75]
	v_mfma_f32_16x16x32_bf16 v[76:79], v[108:111], v[88:91], v[76:79]
	v_mfma_f32_16x16x32_bf16 v[80:83], v[120:123], v[88:91], v[80:83]
	v_mfma_f32_16x16x32_bf16 v[60:63], v[124:127], v[88:91], v[60:63]
	global_load_dwordx4 v[88:91], v[22:23], off offset:128
	s_waitcnt vmcnt(0)
	v_mfma_f32_16x16x32_bf16 v[2:5], v[104:107], v[88:91], v[2:5]
	global_load_dwordx4 v[104:107], v[24:25], off offset:192
	v_mfma_f32_16x16x32_bf16 v[6:9], v[108:111], v[88:91], v[6:9]
	v_mfma_f32_16x16x32_bf16 v[92:95], v[120:123], v[88:91], v[92:95]
	v_mfma_f32_16x16x32_bf16 v[68:71], v[124:127], v[88:91], v[68:71]
	global_load_dwordx4 v[88:91], v[28:29], off offset:192
	s_nop 0
	global_load_dwordx4 v[24:27], v[26:27], off offset:192
	s_nop 0
	global_load_dwordx4 v[28:31], v[30:31], off offset:192
	s_waitcnt vmcnt(0)
	v_mfma_f32_16x16x32_bf16 v[108:111], v[28:31], v[24:27], v[112:115]
	s_nop 2
	global_load_dwordx4 v[112:115], v[32:33], off offset:192
	v_mfma_f32_16x16x32_bf16 v[84:87], v[104:107], v[24:27], v[84:87]
	v_mfma_f32_16x16x32_bf16 v[96:99], v[88:91], v[24:27], v[96:99]
	s_waitcnt vmcnt(0)
	v_mfma_f32_16x16x32_bf16 v[24:27], v[112:115], v[24:27], v[52:55]
	s_nop 2
	global_load_dwordx4 v[52:55], v[18:19], off offset:192
	s_nop 0
	global_load_dwordx4 v[18:21], v[20:21], off offset:192
	s_waitcnt vmcnt(1)
	v_mfma_f32_16x16x32_bf16 v[64:67], v[104:107], v[52:55], v[64:67]
	v_mfma_f32_16x16x32_bf16 v[100:103], v[88:91], v[52:55], v[100:103]
	v_mfma_f32_16x16x32_bf16 v[116:119], v[28:31], v[52:55], v[116:119]
	v_mfma_f32_16x16x32_bf16 v[52:55], v[112:115], v[52:55], v[56:59]
	s_waitcnt vmcnt(0)
	v_mfma_f32_16x16x32_bf16 v[56:59], v[104:107], v[18:21], v[72:75]
	v_mfma_f32_16x16x32_bf16 v[72:75], v[88:91], v[18:21], v[76:79]
	s_nop 2
	global_load_dwordx4 v[76:79], v[22:23], off offset:192
	v_mfma_f32_16x16x32_bf16 v[80:83], v[28:31], v[18:21], v[80:83]
	v_add_u32_e32 v22, s20, v34
	ds_write_b128 v22, v[84:87]
	ds_write_b128 v22, v[96:99] offset:1024
	ds_write_b128 v22, v[108:111] offset:2048
	ds_write_b128 v22, v[24:27] offset:3072
	ds_write_b128 v22, v[64:67] offset:4096
	ds_write_b128 v22, v[100:103] offset:5120
	v_mfma_f32_16x16x32_bf16 v[18:21], v[112:115], v[18:21], v[60:63]
	ds_write_b128 v22, v[116:119] offset:6144
	ds_write_b128 v22, v[52:55] offset:7168
	ds_write_b128 v22, v[56:59] offset:8192
	ds_write_b128 v22, v[72:75] offset:9216
	ds_write_b128 v22, v[80:83] offset:10240
	s_nop 2
	ds_write_b128 v22, v[18:21] offset:11264
	s_waitcnt vmcnt(0)
	v_mfma_f32_16x16x32_bf16 v[2:5], v[104:107], v[76:79], v[2:5]
	v_mfma_f32_16x16x32_bf16 v[6:9], v[88:91], v[76:79], v[6:9]
	v_mfma_f32_16x16x32_bf16 v[18:21], v[28:31], v[76:79], v[92:95]
	s_nop 5
	ds_write_b128 v22, v[2:5] offset:12288
	ds_write_b128 v22, v[6:9] offset:13312
	ds_write_b128 v22, v[18:21] offset:14336
	v_mfma_f32_16x16x32_bf16 v[2:5], v[112:115], v[76:79], v[68:71]
	s_nop 7
	ds_write_b128 v22, v[2:5] offset:15360
	s_waitcnt lgkmcnt(0)
	s_barrier
	s_and_saveexec_b64 s[38:39], s[0:1]
	s_cbranch_execz .LBB0_891
	ds_read_b128 v[4:7], v36
	ds_read_b128 v[18:21], v37 offset:16384
	v_or_b32_e32 v2, s19, v35
	v_lshlrev_b64 v[14:15], 13, v[14:15]
	v_lshl_add_u64 v[14:15], s[68:69], 0, v[14:15]
	s_waitcnt lgkmcnt(0)
	v_pk_add_f32 v[8:9], v[6:7], v[20:21]
	v_pk_add_f32 v[18:19], v[4:5], v[18:19]
	ds_read_b128 v[4:7], v37 offset:32768
	s_waitcnt lgkmcnt(0)
	v_pk_add_f32 v[8:9], v[8:9], v[6:7]
	v_pk_add_f32 v[18:19], v[18:19], v[4:5]
	ds_read_b128 v[4:7], v37 offset:49152
	s_waitcnt lgkmcnt(0)
	v_pk_add_f32 v[8:9], v[8:9], v[6:7]
	v_pk_add_f32 v[18:19], v[18:19], v[4:5]
	ds_read_b128 v[4:7], v38
	s_waitcnt lgkmcnt(0)
	v_pk_add_f32 v[8:9], v[8:9], v[6:7]
	v_pk_add_f32 v[18:19], v[18:19], v[4:5]
	ds_read_b128 v[4:7], v39
	s_waitcnt lgkmcnt(0)
	v_pk_add_f32 v[8:9], v[8:9], v[6:7]
	v_pk_add_f32 v[18:19], v[18:19], v[4:5]
	ds_read_b128 v[4:7], v40
	s_waitcnt lgkmcnt(0)
	v_pk_add_f32 v[8:9], v[8:9], v[6:7]
	v_pk_add_f32 v[18:19], v[18:19], v[4:5]
	ds_read_b128 v[4:7], v41
	s_waitcnt lgkmcnt(0)
	v_pk_add_f32 v[6:7], v[8:9], v[6:7]
	v_pk_add_f32 v[4:5], v[18:19], v[4:5]
	v_pk_mul_f32 v[6:7], v[16:17], v[6:7] op_sel_hi:[0,1]
	v_pk_mul_f32 v[4:5], v[16:17], v[4:5] op_sel_hi:[0,1]
	v_add_u32_e32 v8, v2, v42
	v_max_f32_e32 v5, 0, v5
	v_max_f32_e32 v4, 0, v4
	v_max_f32_e32 v7, 0, v7
	v_max_f32_e32 v6, 0, v6
	v_pk_mul_f32 v[6:7], v[6:7], v[6:7]
	v_pk_mul_f32 v[4:5], v[4:5], v[4:5]
	v_ashrrev_i32_e32 v9, 31, v8
	v_lshl_add_u64 v[8:9], v[8:9], 1, v[14:15]
	v_cvt_pk_bf16_f32 v4, v4, v5
	v_cvt_pk_bf16_f32 v5, v6, v7
	global_store_dwordx2 v[8:9], v[4:5], off
	s_and_b64 exec, exec, s[42:43]
	s_cbranch_execz .LBB0_891
	ds_read_b128 v[4:7], v36 offset:8192
	ds_read_b128 v[18:21], v43 offset:16384
	v_add_u32_e32 v2, v2, v48
	v_ashrrev_i32_e32 v3, 31, v2
	s_waitcnt lgkmcnt(0)
	v_pk_add_f32 v[8:9], v[6:7], v[20:21]
	v_pk_add_f32 v[14:15], v[4:5], v[18:19]
	ds_read_b128 v[4:7], v43 offset:32768
	s_waitcnt lgkmcnt(0)
	v_pk_add_f32 v[8:9], v[8:9], v[6:7]
	v_pk_add_f32 v[14:15], v[14:15], v[4:5]
	ds_read_b128 v[4:7], v43 offset:49152
	s_waitcnt lgkmcnt(0)
	v_pk_add_f32 v[8:9], v[8:9], v[6:7]
	v_pk_add_f32 v[14:15], v[14:15], v[4:5]
	ds_read_b128 v[4:7], v44
	s_waitcnt lgkmcnt(0)
	v_pk_add_f32 v[8:9], v[8:9], v[6:7]
	v_pk_add_f32 v[14:15], v[14:15], v[4:5]
	ds_read_b128 v[4:7], v45
	s_waitcnt lgkmcnt(0)
	v_pk_add_f32 v[8:9], v[8:9], v[6:7]
	v_pk_add_f32 v[14:15], v[14:15], v[4:5]
	ds_read_b128 v[4:7], v46
	s_waitcnt lgkmcnt(0)
	v_pk_add_f32 v[8:9], v[8:9], v[6:7]
	v_pk_add_f32 v[14:15], v[14:15], v[4:5]
	ds_read_b128 v[4:7], v47
	s_waitcnt lgkmcnt(0)
	v_pk_add_f32 v[6:7], v[8:9], v[6:7]
	v_pk_add_f32 v[4:5], v[14:15], v[4:5]
	v_add3_u32 v8, v51, v50, s22
	v_pk_mul_f32 v[6:7], v[0:1], v[6:7] op_sel_hi:[0,1]
	v_pk_mul_f32 v[4:5], v[0:1], v[4:5] op_sel_hi:[0,1]
	v_ashrrev_i32_e32 v9, 31, v8
	v_max_f32_e32 v5, 0, v5
	v_max_f32_e32 v4, 0, v4
	v_max_f32_e32 v7, 0, v7
	v_max_f32_e32 v6, 0, v6
	v_lshlrev_b64 v[8:9], 13, v[8:9]
	v_pk_mul_f32 v[6:7], v[6:7], v[6:7]
	v_pk_mul_f32 v[4:5], v[4:5], v[4:5]
	v_lshl_add_u64 v[8:9], s[68:69], 0, v[8:9]
	v_lshl_add_u64 v[2:3], v[2:3], 1, v[8:9]
	v_cvt_pk_bf16_f32 v4, v4, v5
	v_cvt_pk_bf16_f32 v5, v6, v7
	global_store_dwordx2 v[2:3], v[4:5], off
	s_branch .LBB0_891
